# M2 compression-bias dot product: 32 rows loaded per trip with counted waits instead of one wait per 4-byte load
# speedup vs baseline: 1.0742x; 1.0177x over previous
.LBB0_880:
	s_add_u32 s12, s7, s34
	s_addc_u32 s13, s10, s35
	s_add_u32 s38, s12, 0x2000
	s_addc_u32 s39, s13, 0
	global_load_dwordx4 v[24:27], v1, s[38:39] offset:16
	global_load_dwordx4 v[20:23], v192, s[12:13]
	global_load_dwordx4 v[32:35], v1, s[38:39] offset:48
	global_load_dwordx4 v[28:31], v192, s[12:13] offset:32
	global_load_dwordx4 v[40:43], v1, s[38:39] offset:80
	global_load_dwordx4 v[36:39], v192, s[12:13] offset:64
	global_load_dwordx4 v[48:51], v1, s[38:39] offset:112
	global_load_dwordx4 v[44:47], v192, s[12:13] offset:96
	s_add_u32 s38, s30, 0x200000
	s_addc_u32 s39, s31, 0
	global_load_dword v52, v0, s[38:39]
	global_load_dword v53, v0, s[38:39] offset:1024
	global_load_dword v54, v0, s[38:39] offset:2048
	global_load_dword v55, v0, s[38:39] offset:3072
	s_add_u32 s12, s30, 0x201000
	s_addc_u32 s13, s31, 0
	global_load_dword v56, v0, s[12:13]
	global_load_dword v57, v0, s[12:13] offset:1024
	global_load_dword v58, v0, s[12:13] offset:2048
	global_load_dword v59, v0, s[12:13] offset:3072
	s_add_u32 s38, s30, 0x202000
	s_addc_u32 s39, s31, 0
	global_load_dword v60, v0, s[38:39]
	global_load_dword v61, v0, s[38:39] offset:1024
	global_load_dword v62, v0, s[38:39] offset:2048
	global_load_dword v63, v0, s[38:39] offset:3072
	s_add_u32 s12, s30, 0x203000
	s_addc_u32 s13, s31, 0
	global_load_dword v64, v0, s[12:13]
	global_load_dword v65, v0, s[12:13] offset:1024
	global_load_dword v66, v0, s[12:13] offset:2048
	global_load_dword v67, v0, s[12:13] offset:3072
	s_add_u32 s38, s30, 0x204000
	s_addc_u32 s39, s31, 0
	global_load_dword v68, v0, s[38:39]
	global_load_dword v69, v0, s[38:39] offset:1024
	global_load_dword v70, v0, s[38:39] offset:2048
	global_load_dword v71, v0, s[38:39] offset:3072
	s_add_u32 s12, s30, 0x205000
	s_addc_u32 s13, s31, 0
	global_load_dword v72, v0, s[12:13]
	global_load_dword v73, v0, s[12:13] offset:1024
	global_load_dword v74, v0, s[12:13] offset:2048
	global_load_dword v75, v0, s[12:13] offset:3072
	s_add_u32 s38, s30, 0x206000
	s_addc_u32 s39, s31, 0
	global_load_dword v76, v0, s[38:39]
	global_load_dword v77, v0, s[38:39] offset:1024
	global_load_dword v78, v0, s[38:39] offset:2048
	global_load_dword v79, v0, s[38:39] offset:3072
	s_add_u32 s12, s30, 0x207000
	s_addc_u32 s13, s31, 0
	global_load_dword v80, v0, s[12:13]
	global_load_dword v81, v0, s[12:13] offset:1024
	global_load_dword v82, v0, s[12:13] offset:2048
	global_load_dword v83, v0, s[12:13] offset:3072
	s_add_u32 s34, s34, 0x80
	s_addc_u32 s35, s35, 0
	s_add_u32 s30, s30, 0x8000
	s_addc_u32 s31, s31, 0
	s_cmpk_eq_i32 s34, 0x400
	s_waitcnt vmcnt(31)
	v_fmac_f32_e32 v3, v20, v52
	s_waitcnt vmcnt(30)
	v_fmac_f32_e32 v3, v21, v53
	s_waitcnt vmcnt(29)
	v_fmac_f32_e32 v3, v22, v54
	s_waitcnt vmcnt(28)
	v_fmac_f32_e32 v3, v23, v55
	s_waitcnt vmcnt(27)
	v_fmac_f32_e32 v3, v24, v56
	s_waitcnt vmcnt(26)
	v_fmac_f32_e32 v3, v25, v57
	s_waitcnt vmcnt(25)
	v_fmac_f32_e32 v3, v26, v58
	s_waitcnt vmcnt(24)
	v_fmac_f32_e32 v3, v27, v59
	s_waitcnt vmcnt(23)
	v_fmac_f32_e32 v3, v28, v60
	s_waitcnt vmcnt(22)
	v_fmac_f32_e32 v3, v29, v61
	s_waitcnt vmcnt(21)
	v_fmac_f32_e32 v3, v30, v62
	s_waitcnt vmcnt(20)
	v_fmac_f32_e32 v3, v31, v63
	s_waitcnt vmcnt(19)
	v_fmac_f32_e32 v3, v32, v64
	s_waitcnt vmcnt(18)
	v_fmac_f32_e32 v3, v33, v65
	s_waitcnt vmcnt(17)
	v_fmac_f32_e32 v3, v34, v66
	s_waitcnt vmcnt(16)
	v_fmac_f32_e32 v3, v35, v67
	s_waitcnt vmcnt(15)
	v_fmac_f32_e32 v3, v36, v68
	s_waitcnt vmcnt(14)
	v_fmac_f32_e32 v3, v37, v69
	s_waitcnt vmcnt(13)
	v_fmac_f32_e32 v3, v38, v70
	s_waitcnt vmcnt(12)
	v_fmac_f32_e32 v3, v39, v71
	s_waitcnt vmcnt(11)
	v_fmac_f32_e32 v3, v40, v72
	s_waitcnt vmcnt(10)
	v_fmac_f32_e32 v3, v41, v73
	s_waitcnt vmcnt(9)
	v_fmac_f32_e32 v3, v42, v74
	s_waitcnt vmcnt(8)
	v_fmac_f32_e32 v3, v43, v75
	s_waitcnt vmcnt(7)
	v_fmac_f32_e32 v3, v44, v76
	s_waitcnt vmcnt(6)
	v_fmac_f32_e32 v3, v45, v77
	s_waitcnt vmcnt(5)
	v_fmac_f32_e32 v3, v46, v78
	s_waitcnt vmcnt(4)
	v_fmac_f32_e32 v3, v47, v79
	s_waitcnt vmcnt(3)
	v_fmac_f32_e32 v3, v48, v80
	s_waitcnt vmcnt(2)
	v_fmac_f32_e32 v3, v49, v81
	s_waitcnt vmcnt(1)
	v_fmac_f32_e32 v3, v50, v82
	s_waitcnt vmcnt(0)
	v_fmac_f32_e32 v3, v51, v83
	s_cbranch_scc0 .LBB0_880
	s_lshl_b32 s6, s6, 5
	s_and_b32 s6, s6, 0xffffff00
	v_or_b32_e32 v0, s6, v2
	v_readlane_b32 s6, v249, 44
	v_readlane_b32 s7, v249, 45
	s_mov_b32 s17, s14
	s_nop 0
	v_lshl_add_u64 v[4:5], v[0:1], 2, s[6:7]
	global_store_dword v[4:5], v3, off
